# v11 + final rmsnorm row loop software-prefetches the next row (loads issued before the current row's stores, counted vmcnt(8) at the loop bottom); bit-identical
# speedup vs baseline: 1.0044x; 1.0044x over previous
; __device__ __forceinline__ float bf_lo(unsigned w) { return __uint_as_float(w << 16); }
; __device__ __forceinline__ float bf_hi(unsigned w) { return __uint_as_float(w & 0xffff0000u); }
; template <bool MOD, bool SRC16>
; __device__ __forceinline__ void norm_rows(const float* src, int nrows, int tok0, const float* g, const float* ada, int sh_off, int sc_off, bf16* dst, float* dstf, int gw, int NGW, int lane_in) {
;     ...
;     for (int m = gw; m < nrows; m += NGW) {
;         f32x4 v[8]; float s = 0.f;
;         if (SRC16) { const v4u* xh = (const v4u*)((const bf16*)src + (size_t)m * 4096) + lane;
; #pragma unroll
;             for (int j = 0; j < 4; ++j) { const v4u w = xh[64 * j]; v[2 * j] = (f32x4){pg8::bf_lo(w.x), pg8::bf_hi(w.x), pg8::bf_lo(w.y), pg8::bf_hi(w.y)}; v[2 * j + 1] = (f32x4){pg8::bf_lo(w.z), pg8::bf_hi(w.z), pg8::bf_lo(w.w), pg8::bf_hi(w.w)}; } }
;         else { const f32x4* xr = (const f32x4*)(src + (size_t)m * DM) + lane;
; #pragma unroll
;             for (int j = 0; j < 8; ++j) v[j] = __builtin_nontemporal_load(xr + 64 * j); }
.LBB0_2149:
	s_or_b64 exec, exec, s[0:1]
	v_readlane_b32 s8, v248, 39
	s_cmp_gt_i32 s8, 0xbfff
	s_waitcnt lgkmcnt(0)
	s_barrier
	v_readlane_b32 s9, v248, 40
	s_cbranch_scc1 .LBB0_2152
	v_lshlrev_b32_e32 v12, 3, v192
	v_ashrrev_i32_e32 v13, 31, v12
	v_lshlrev_b64 v[0:1], 2, v[12:13]
	v_add_u32_e32 v4, 0x200, v12
	v_add_u32_e32 v8, 0x400, v12
	v_add_u32_e32 v12, 0x600, v12
	v_readlane_b32 s0, v248, 3
	v_ashrrev_i32_e32 v5, 31, v4
	v_ashrrev_i32_e32 v9, 31, v8
	v_ashrrev_i32_e32 v13, 31, v12
	v_readlane_b32 s1, v248, 4
	v_lshlrev_b64 v[4:5], 2, v[4:5]
	v_lshlrev_b64 v[8:9], 2, v[8:9]
	v_lshlrev_b64 v[12:13], 2, v[12:13]
	s_ashr_i32 s9, s8, 31
	v_readlane_b32 s2, v248, 5
	v_lshl_add_u64 v[2:3], s[0:1], 0, v[0:1]
	v_lshl_add_u64 v[6:7], s[0:1], 0, v[4:5]
	v_lshl_add_u64 v[10:11], s[0:1], 0, v[8:9]
	v_lshl_add_u64 v[14:15], s[0:1], 0, v[12:13]
	s_lshl_b64 s[0:1], s[8:9], 13
	v_readlane_b32 s3, v248, 6
	s_add_u32 s2, s2, s0
	v_ashrrev_i32_e32 v193, 31, v192
	s_addc_u32 s3, s3, s1
	s_ashr_i32 s87, s86, 31
	v_or_b32_e32 v12, 16, v12
	s_lshl_b64 s[4:5], s[86:87], 13
	v_lshlrev_b64 v[16:17], 4, v[192:193]
	v_or_b32_e32 v4, 16, v4
	v_or_b32_e32 v8, 16, v8
	v_mov_b32_e32 v20, 0x358637bd
	s_mov_b32 s6, 0xf800000
	v_mov_b32_e32 v21, 0x260
	global_load_dwordx4 v[100:103], v[2:3], off
	global_load_dwordx4 v[104:107], v[2:3], off offset:16
	global_load_dwordx4 v[108:111], v[2:3], off offset:2048
	global_load_dwordx4 v[112:115], v[6:7], off offset:16
	global_load_dwordx4 v[116:119], v[10:11], off
	global_load_dwordx4 v[120:123], v[10:11], off offset:16
	global_load_dwordx4 v[124:127], v[14:15], off
	global_load_dwordx4 v[128:131], v[14:15], off offset:16
	s_waitcnt vmcnt(0)
	v_lshl_add_u64 v[18:19], s[2:3], 0, v[16:17]
	global_load_dwordx4 v[140:143], v[18:19], off offset:1024
	global_load_dwordx4 v[144:147], v[18:19], off offset:2048
	global_load_dwordx4 v[148:151], v[18:19], off offset:3072
	global_load_dwordx4 v[136:139], v[18:19], off
	s_waitcnt vmcnt(0)
.LBB0_2151:
	v_mov_b64_e32 v[26:27], v[140:141]
	v_mov_b64_e32 v[28:29], v[142:143]
	v_mov_b64_e32 v[30:31], v[144:145]
	v_mov_b64_e32 v[32:33], v[146:147]
	v_mov_b64_e32 v[34:35], v[148:149]
	v_mov_b64_e32 v[36:37], v[150:151]
	v_mov_b64_e32 v[38:39], v[136:137]
	v_mov_b64_e32 v[40:41], v[138:139]
	v_lshl_add_u64 v[42:43], s[2:3], 0, v[0:1]
	s_add_i32 s8, s8, s86
	s_cmp_lt_i32 s8, 0xc000
	s_cbranch_scc0 .Lj_nopf
	s_add_u32 s0, s2, s4
	s_addc_u32 s1, s3, s5
	v_lshl_add_u64 v[18:19], s[0:1], 0, v[16:17]
	global_load_dwordx4 v[140:143], v[18:19], off offset:1024
	global_load_dwordx4 v[144:147], v[18:19], off offset:2048
	global_load_dwordx4 v[148:151], v[18:19], off offset:3072
	global_load_dwordx4 v[136:139], v[18:19], off
; __device__ __forceinline__ float wave_sum(float v) {
; #pragma unroll
;     for (int o = 1; o < 64; o <<= 1) v += __shfl_xor(v, o);
;     return v;
; }
; template <bool MOD, bool SRC16>
; __device__ __forceinline__ void norm_rows(const float* src, int nrows, int tok0, const float* g, const float* ada, int sh_off, int sc_off, bf16* dst, float* dstf, int gw, int NGW, int lane_in) {
;     ...
;         if (SRC16) { const v4u* xh = (const v4u*)((const bf16*)src + (size_t)m * 4096) + lane;
; #pragma unroll
;             for (int j = 0; j < 4; ++j) { const v4u w = xh[64 * j]; v[2 * j] = (f32x4){pg8::bf_lo(w.x), pg8::bf_hi(w.x), pg8::bf_lo(w.y), pg8::bf_hi(w.y)}; v[2 * j + 1] = (f32x4){pg8::bf_lo(w.z), pg8::bf_hi(w.z), pg8::bf_lo(w.w), pg8::bf_hi(w.w)}; } }
;         else { const f32x4* xr = (const f32x4*)(src + (size_t)m * DM) + lane;
; #pragma unroll
;             for (int j = 0; j < 8; ++j) v[j] = __builtin_nontemporal_load(xr + 64 * j); }
; #pragma unroll
;         for (int j = 0; j < 8; ++j) { s += (v[j].x * v[j].x + v[j].y * v[j].y) + (v[j].z * v[j].z + v[j].w * v[j].w); }
;         const float r = 1.0f / sqrtf(wave_sum(s) * (1.f / DM) + EPS);
;         if (MOD) {
;             const int b = batch_of(tok0 + m); const float* ab = ada + (size_t)b * ADAW;
;             f32x4 y[8];
; #pragma unroll
;             for (int j = 0; j < 8; ++j) { const int col = SRC16 ? 8 * (lane + 64 * (j >> 1)) + 4 * (j & 1) : 4 * (lane + 64 * j);
;                 const f32x4 gv = *(const f32x4*)(g + col), sc = *(const f32x4*)(ab + sc_off + col), sh = *(const f32x4*)(ab + sh_off + col);
;                 y[j] = (v[j] * r) * gv * (sc + 1.0f) + sh; }
;             if (SRC16) { v4u* o16 = (v4u*)(dst + (size_t)m * DM) + lane;
; #pragma unroll
;                 for (int j = 0; j < 4; ++j) { v4u w; w.x = pk2(y[2 * j].x, y[2 * j].y); w.y = pk2(y[2 * j].z, y[2 * j].w); w.z = pk2(y[2 * j + 1].x, y[2 * j + 1].y); w.w = pk2(y[2 * j + 1].z, y[2 * j + 1].w); o16[64 * j] = w; } }
;             else { v2u* o8 = (v2u*)(dst + (size_t)m * DM) + lane;
; #pragma unroll
;                 for (int j = 0; j < 8; ++j) { v2u w; w.x = pk2(y[j].x, y[j].y); w.y = pk2(y[j].z, y[j].w); o8[64 * j] = w; } }
;         } else {
; #pragma unroll
;             for (int j = 0; j < 8; ++j) { const int col = SRC16 ? 8 * (lane + 64 * (j >> 1)) + 4 * (j & 1) : 4 * (lane + 64 * j);
.Lj_nopf:
	v_lshlrev_b32_e32 v44, 16, v28
	v_and_b32_e32 v45, 0xffff0000, v28
	v_lshlrev_b32_e32 v28, 16, v30
	v_lshlrev_b32_e32 v49, 16, v40
	v_and_b32_e32 v51, 0xffff0000, v40
	v_and_b32_e32 v50, 0xffff0000, v38
	v_lshlrev_b32_e32 v53, 16, v41
	v_and_b32_e32 v41, 0xffff0000, v41
	v_and_b32_e32 v40, 0xffff0000, v39
	v_lshlrev_b32_e32 v48, 16, v38
	v_lshlrev_b32_e32 v52, 16, v39
	v_lshlrev_b32_e32 v39, 16, v27
	v_lshlrev_b32_e32 v38, 16, v26
	v_and_b32_e32 v27, 0xffff0000, v27
	v_and_b32_e32 v26, 0xffff0000, v26
	v_pk_mul_f32 v[58:59], v[50:51], v[50:51]
	v_pk_mul_f32 v[60:61], v[40:41], v[40:41]
	v_lshlrev_b32_e32 v54, 16, v29
	v_pk_mul_f32 v[62:63], v[26:27], v[26:27]
	v_pk_fma_f32 v[58:59], v[48:49], v[48:49], v[58:59]
	v_pk_fma_f32 v[60:61], v[52:53], v[52:53], v[60:61]
	v_and_b32_e32 v55, 0xffff0000, v29
	v_mul_f32_e32 v29, v44, v44
	v_mul_f32_e32 v65, v45, v45
	v_mul_f32_e32 v66, v54, v54
	v_mov_b32_e32 v64, v28
	v_pk_fma_f32 v[62:63], v[38:39], v[38:39], v[62:63]
	v_pk_add_f32 v[58:59], v[58:59], v[60:61]
	v_and_b32_e32 v82, 0xffff0000, v30
	v_lshlrev_b32_e32 v30, 16, v31
	v_and_b32_e32 v31, 0xffff0000, v31
	v_pk_fma_f32 v[66:67], v[54:55], v[54:55], v[66:67] op_sel_hi:[1,1,0]
	v_pk_add_f32 v[64:65], v[28:29], v[64:65]
	v_pk_add_f32 v[60:61], v[62:63], v[62:63] op_sel_hi:[0,1]
	v_pk_add_f32 v[58:59], v[58:59], v[58:59] op_sel_hi:[0,1]
	v_lshlrev_b32_e32 v57, 16, v33
	v_lshlrev_b32_e32 v56, 16, v32
	v_and_b32_e32 v33, 0xffff0000, v33
	v_and_b32_e32 v32, 0xffff0000, v32
	v_mul_f32_e32 v68, v28, v28
	v_mul_f32_e32 v66, v82, v82
	v_mov_b32_e32 v69, v65
	v_mul_f32_e32 v60, v31, v31
	v_mul_f32_e32 v58, v30, v30
	v_lshlrev_b32_e32 v46, 16, v34
	v_and_b32_e32 v47, 0xffff0000, v34
	v_lshlrev_b32_e32 v18, 16, v36
	v_lshlrev_b32_e32 v34, 16, v35
	v_pk_mul_f32 v[70:71], v[32:33], v[32:33]
	v_pk_add_f32 v[64:65], v[68:69], v[66:67]
	v_pk_add_f32 v[58:59], v[58:59], v[60:61]
	v_and_b32_e32 v35, 0xffff0000, v35
	v_mul_f32_e32 v19, v46, v46
	v_mul_f32_e32 v73, v47, v47
	v_mul_f32_e32 v74, v34, v34
	v_mov_b32_e32 v72, v18
	v_pk_fma_f32 v[70:71], v[56:57], v[56:57], v[70:71]
	v_pk_add_f32 v[58:59], v[64:65], v[58:59]
	v_and_b32_e32 v83, 0xffff0000, v36
	v_lshlrev_b32_e32 v36, 16, v37
	v_and_b32_e32 v37, 0xffff0000, v37
	v_pk_fma_f32 v[74:75], v[34:35], v[34:35], v[74:75] op_sel_hi:[1,1,0]
	v_pk_add_f32 v[72:73], v[18:19], v[72:73]
	v_pk_add_f32 v[62:63], v[70:71], v[70:71] op_sel_hi:[0,1]
	v_pk_add_f32 v[58:59], v[58:59], v[58:59] op_sel_hi:[0,1]
	v_mul_f32_e32 v76, v18, v18
	v_mul_f32_e32 v74, v83, v83
	v_mov_b32_e32 v77, v73
	v_mul_f32_e32 v62, v36, v36
	v_mul_f32_e32 v58, v37, v37
	v_pk_add_f32 v[66:67], v[76:77], v[74:75]
	v_pk_add_f32 v[58:59], v[62:63], v[58:59]
	v_mov_b32_e32 v81, v40
	v_pk_add_f32 v[58:59], v[66:67], v[58:59]
	v_mov_b32_e32 v78, v48
	v_add_f32_e32 v19, v58, v59
	ds_bpermute_b32 v29, v195, v19
	v_mov_b32_e32 v79, v50
	v_mov_b32_e32 v80, v52
	s_waitcnt lgkmcnt(0)
	v_add_f32_e32 v19, v19, v29
	ds_bpermute_b32 v29, v202, v19
	s_waitcnt lgkmcnt(0)
	v_add_f32_e32 v19, v19, v29
	ds_bpermute_b32 v29, v203, v19
	s_waitcnt lgkmcnt(0)
	v_add_f32_e32 v19, v19, v29
	ds_bpermute_b32 v29, v204, v19
	s_waitcnt lgkmcnt(0)
	v_add_f32_e32 v19, v19, v29
	ds_bpermute_b32 v29, v205, v19
	s_waitcnt lgkmcnt(0)
	v_add_f32_e32 v19, v19, v29
	ds_bpermute_b32 v29, v206, v19
	s_waitcnt lgkmcnt(0)
	v_add_f32_e32 v19, v19, v29
	v_fmamk_f32 v19, v19, 0x3a000000, v20
	v_mul_f32_e32 v29, 0x4f800000, v19
	v_cmp_gt_f32_e32 vcc, s6, v19
	s_nop 1
	v_cndmask_b32_e32 v19, v19, v29, vcc
	v_sqrt_f32_e32 v29, v19
	s_nop 0
	v_add_u32_e32 v40, -1, v29
	v_add_u32_e32 v48, 1, v29
	v_fma_f32 v50, -v40, v29, v19
	v_fma_f32 v52, -v48, v29, v19
	v_cmp_ge_f32_e64 s[0:1], 0, v50
	s_nop 1
	v_cndmask_b32_e64 v29, v29, v40, s[0:1]
	v_cmp_lt_f32_e64 s[0:1], 0, v52
	s_nop 1
	v_cndmask_b32_e64 v29, v29, v48, s[0:1]
	v_mul_f32_e32 v40, 0x37800000, v29
	v_cndmask_b32_e32 v29, v29, v40, vcc
	v_cmp_class_f32_e32 vcc, v19, v21
	s_nop 1
	v_cndmask_b32_e32 v19, v29, v19, vcc
	v_div_scale_f32 v29, s[0:1], v19, v19, 1.0
	v_rcp_f32_e32 v48, v29
	v_div_scale_f32 v40, vcc, 1.0, v19, 1.0
	v_fma_f32 v50, -v29, v48, 1.0
	v_fmac_f32_e32 v48, v50, v48
	v_mul_f32_e32 v50, v40, v48
	v_fma_f32 v52, -v29, v50, v40
	v_fmac_f32_e32 v50, v52, v48
	v_fma_f32 v29, -v29, v50, v40
	v_div_fmas_f32 v29, v29, v48, v50
	v_div_fixup_f32 v48, v29, v19, 1.0
	v_pk_mul_f32 v[58:59], v[78:79], v[48:49] op_sel_hi:[1,0]
	v_pk_mul_f32 v[60:61], v[80:81], v[48:49] op_sel_hi:[1,0]
	v_pk_mul_f32 v[22:23], v[100:101], v[58:59]
	v_pk_mul_f32 v[24:25], v[102:103], v[60:61]
	global_store_dwordx4 v[42:43], v[22:25], off
	v_mov_b32_e32 v40, v53
	v_mov_b32_e32 v50, v49
	v_pk_mul_f32 v[40:41], v[40:41], v[48:49] op_sel_hi:[1,0]
	v_pk_mul_f32 v[50:51], v[50:51], v[48:49] op_sel_hi:[1,0]
	v_mov_b32_e32 v29, v82
	v_pk_mul_f32 v[30:31], v[30:31], v[48:49] op_sel_hi:[1,0]
	v_pk_mul_f32 v[28:29], v[28:29], v[48:49] op_sel_hi:[1,0]
	v_mov_b32_e32 v19, v83
	v_pk_mul_f32 v[18:19], v[18:19], v[48:49] op_sel_hi:[1,0]
	v_pk_mul_f32 v[132:133], v[104:105], v[50:51]
	v_pk_mul_f32 v[134:135], v[106:107], v[40:41]
	global_store_dwordx4 v[42:43], v[132:135], off offset:16
	v_mov_b32_e32 v40, v39
	v_mov_b32_e32 v41, v27
	v_mov_b32_e32 v39, v26
	v_pk_mul_f32 v[26:27], v[48:49], v[40:41] op_sel_hi:[0,1]
	v_pk_mul_f32 v[38:39], v[48:49], v[38:39] op_sel_hi:[0,1]
	v_pk_mul_f32 v[40:41], v[44:45], v[48:49] op_sel_hi:[1,0]
	v_pk_mul_f32 v[22:23], v[108:109], v[38:39]
	v_pk_mul_f32 v[24:25], v[110:111], v[26:27]
	global_store_dwordx4 v[42:43], v[22:25], off offset:2048
	v_pk_mul_f32 v[38:39], v[54:55], v[48:49] op_sel_hi:[1,0]
	v_lshl_add_u64 v[26:27], s[2:3], 0, v[4:5]
	v_pk_mul_f32 v[132:133], v[112:113], v[40:41]
	v_pk_mul_f32 v[134:135], v[114:115], v[38:39]
	global_store_dwordx4 v[26:27], v[132:135], off
	v_lshl_add_u64 v[26:27], s[2:3], 0, v[8:9]
	v_pk_mul_f32 v[22:23], v[116:117], v[28:29]
	v_pk_mul_f32 v[24:25], v[118:119], v[30:31]
	global_store_dwordx4 v[26:27], v[22:25], off offset:-16
	v_mov_b32_e32 v28, v57
	v_mov_b32_e32 v29, v33
	v_mov_b32_e32 v57, v32
	v_pk_mul_f32 v[28:29], v[48:49], v[28:29] op_sel_hi:[0,1]
	v_pk_mul_f32 v[30:31], v[48:49], v[56:57] op_sel_hi:[0,1]
	v_pk_mul_f32 v[132:133], v[120:121], v[30:31]
	v_pk_mul_f32 v[134:135], v[122:123], v[28:29]
	global_store_dwordx4 v[26:27], v[132:135], off
	v_pk_mul_f32 v[28:29], v[34:35], v[48:49] op_sel_hi:[1,0]
	v_pk_mul_f32 v[30:31], v[46:47], v[48:49] op_sel_hi:[1,0]
	v_lshl_add_u64 v[26:27], s[2:3], 0, v[12:13]
	s_add_u32 s2, s2, s4
	s_addc_u32 s3, s3, s5
	s_cmp_lt_i32 s8, 0xc000
	v_pk_mul_f32 v[22:23], v[124:125], v[30:31]
	v_pk_mul_f32 v[24:25], v[126:127], v[28:29]
	global_store_dwordx4 v[26:27], v[22:25], off offset:-16
	v_pk_mul_f32 v[28:29], v[36:37], v[48:49] op_sel_hi:[1,0]
	v_pk_mul_f32 v[132:133], v[128:129], v[18:19]
	v_pk_mul_f32 v[134:135], v[130:131], v[28:29]
	global_store_dwordx4 v[26:27], v[132:135], off
	s_waitcnt vmcnt(8)
	s_cbranch_scc1 .LBB0_2151
